# grid barrier: poll back-off shortened (s_sleep 8 -> s_sleep 2) in the 20 release-poll loops
# baseline (speedup 1.0000x reference)
.LBB0_348:
	s_and_b32 s1, s0, 0xff
	s_mov_b64 s[42:43], -1
	s_cmp_lg_u32 s1, 0
	s_mov_b64 s[68:69], -1
	s_sleep 2
	s_cbranch_scc0 .LBB0_351
	s_and_b64 vcc, exec, s[68:69]
	s_cbranch_vccz .LBB0_347

.LBB0_442:
	s_and_b32 s1, s0, 0xff
	s_mov_b64 s[38:39], -1
	s_cmp_lg_u32 s1, 0
	s_mov_b64 s[42:43], -1
	s_sleep 2
	s_cbranch_scc0 .LBB0_445
	s_and_b64 vcc, exec, s[42:43]
	s_cbranch_vccz .LBB0_441
